# sequence-DFT output stage: 32 flat_store_short_d16_hi replaced by global_store_short_d16_hi (no lgkmcnt coupling, job-end lgkmcnt(0) no longer waits for store completion)
# speedup vs baseline: 1.0010x; 1.0010x over previous
.LBB0_1229:
	v_lshl_add_u64 v[152:153], v[150:151], 0, s[0:1]
	v_add_co_u32_e32 v152, vcc, s57, v152
	v_add_u32_e32 v186, 0x400, v169
	s_nop 0
	v_addc_co_u32_e32 v153, vcc, 0, v153, vcc
	global_load_dwordx4 v[170:173], v[152:153], off
	global_load_dwordx4 v[188:191], v[152:153], off offset:32
	global_load_dwordx4 v[192:195], v[152:153], off offset:64
	global_load_dwordx4 v[196:199], v[152:153], off offset:96
	ds_read2_b32 v[182:183], v169 offset1:32
	ds_read2_b32 v[174:175], v169 offset0:128 offset1:160
	ds_read2_b32 v[184:185], v186 offset1:32
	ds_read2_b32 v[176:177], v186 offset0:128 offset1:160
	v_add_u32_e32 v187, 0x1400, v169
	s_add_u32 s0, s0, 0x80
	s_waitcnt lgkmcnt(3)
	v_mov_b32_e32 v178, v182
	s_waitcnt lgkmcnt(2)
	v_mov_b32_e32 v179, v174
	s_waitcnt lgkmcnt(0)
	v_mov_b32_e32 v181, v176
	v_mov_b32_e32 v174, v183
	v_mov_b32_e32 v176, v185
	v_mov_b32_e32 v180, v184
	s_addc_u32 s1, s1, 0
	s_cmpk_lg_i32 s0, 0x200
	s_waitcnt vmcnt(3)
	v_mfma_f32_32x32x16_bf16 v[32:47], v[170:173], v[174:177], v[32:47]
	ds_read2_b32 v[182:183], v169 offset0:64 offset1:96
	ds_read2_b32 v[174:175], v169 offset0:192 offset1:224
	ds_read2_b32 v[184:185], v186 offset0:64 offset1:96
	ds_read2_b32 v[176:177], v186 offset0:192 offset1:224
	v_add_u32_e32 v186, 0x1000, v169
	v_mfma_f32_32x32x16_bf16 v[48:63], v[170:173], v[178:181], v[48:63]
	s_waitcnt lgkmcnt(3)
	v_mov_b32_e32 v178, v182
	s_waitcnt lgkmcnt(2)
	v_mov_b32_e32 v179, v174
	s_waitcnt lgkmcnt(1)
	v_mov_b32_e32 v180, v184
	s_waitcnt lgkmcnt(0)
	v_mov_b32_e32 v181, v176
	v_mov_b32_e32 v174, v183
	v_mov_b32_e32 v176, v185
	v_mfma_f32_32x32x16_bf16 v[16:31], v[170:173], v[178:181], v[16:31]
	s_nop 0
	v_mfma_f32_32x32x16_bf16 v[0:15], v[170:173], v[174:177], v[0:15]
	ds_read2_b32 v[182:183], v186 offset1:32
	ds_read2_b32 v[174:175], v186 offset0:128 offset1:160
	ds_read2_b32 v[184:185], v187 offset1:32
	ds_read2_b32 v[176:177], v187 offset0:128 offset1:160
	s_waitcnt lgkmcnt(3)
	v_mov_b32_e32 v178, v182
	s_waitcnt lgkmcnt(2)
	v_mov_b32_e32 v179, v174
	s_waitcnt lgkmcnt(0)
	v_mov_b32_e32 v181, v176
	v_mov_b32_e32 v174, v183
	v_mov_b32_e32 v176, v185
	v_mov_b32_e32 v180, v184
	s_waitcnt vmcnt(2)
	v_mfma_f32_32x32x16_bf16 v[32:47], v[188:191], v[174:177], v[32:47]
	ds_read2_b32 v[182:183], v186 offset0:64 offset1:96
	ds_read2_b32 v[174:175], v186 offset0:192 offset1:224
	ds_read2_b32 v[184:185], v187 offset0:64 offset1:96
	ds_read2_b32 v[176:177], v187 offset0:192 offset1:224
	v_add_u32_e32 v186, 0x2000, v169
	v_add_u32_e32 v187, 0x2400, v169
	v_mfma_f32_32x32x16_bf16 v[48:63], v[188:191], v[178:181], v[48:63]
	s_waitcnt lgkmcnt(3)
	v_mov_b32_e32 v178, v182
	s_waitcnt lgkmcnt(2)
	v_mov_b32_e32 v179, v174
	s_waitcnt lgkmcnt(1)
	v_mov_b32_e32 v180, v184
	s_waitcnt lgkmcnt(0)
	v_mov_b32_e32 v181, v176
	v_mov_b32_e32 v174, v183
	v_mov_b32_e32 v176, v185
	v_mfma_f32_32x32x16_bf16 v[16:31], v[188:191], v[178:181], v[16:31]
	s_nop 0
	v_mfma_f32_32x32x16_bf16 v[0:15], v[188:191], v[174:177], v[0:15]
	ds_read2_b32 v[182:183], v186 offset1:32
	ds_read2_b32 v[174:175], v186 offset0:128 offset1:160
	ds_read2_b32 v[184:185], v187 offset1:32
	ds_read2_b32 v[176:177], v187 offset0:128 offset1:160
	s_waitcnt lgkmcnt(3)
	v_mov_b32_e32 v178, v182
	s_waitcnt lgkmcnt(2)
	v_mov_b32_e32 v179, v174
	s_waitcnt lgkmcnt(0)
	v_mov_b32_e32 v181, v176
	v_mov_b32_e32 v174, v183
	v_mov_b32_e32 v176, v185
	v_mov_b32_e32 v180, v184
	s_waitcnt vmcnt(1)
	v_mfma_f32_32x32x16_bf16 v[32:47], v[192:195], v[174:177], v[32:47]
	ds_read2_b32 v[182:183], v186 offset0:64 offset1:96
	ds_read2_b32 v[174:175], v186 offset0:192 offset1:224
	ds_read2_b32 v[184:185], v187 offset0:64 offset1:96
	ds_read2_b32 v[176:177], v187 offset0:192 offset1:224
	v_mfma_f32_32x32x16_bf16 v[48:63], v[192:195], v[178:181], v[48:63]
	s_waitcnt lgkmcnt(3)
	v_mov_b32_e32 v178, v182
	s_waitcnt lgkmcnt(2)
	v_mov_b32_e32 v179, v174
	s_waitcnt lgkmcnt(1)
	v_mov_b32_e32 v180, v184
	s_waitcnt lgkmcnt(0)
	v_mov_b32_e32 v181, v176
	v_mov_b32_e32 v174, v183
	v_mov_b32_e32 v176, v185
	v_add_u32_e32 v184, 0x3000, v169
	v_mfma_f32_32x32x16_bf16 v[16:31], v[192:195], v[178:181], v[16:31]
	v_add_u32_e32 v185, 0x3400, v169
	v_add_u32_e32 v169, 0x4000, v169
	v_mfma_f32_32x32x16_bf16 v[0:15], v[192:195], v[174:177], v[0:15]
	ds_read2_b32 v[152:153], v184 offset1:32
	ds_read2_b32 v[174:175], v184 offset0:128 offset1:160
	ds_read2_b32 v[182:183], v185 offset1:32
	ds_read2_b32 v[176:177], v185 offset0:128 offset1:160
	s_waitcnt lgkmcnt(3)
	v_mov_b32_e32 v178, v152
	s_waitcnt lgkmcnt(2)
	v_mov_b32_e32 v179, v174
	s_waitcnt lgkmcnt(0)
	v_mov_b32_e32 v181, v176
	v_mov_b32_e32 v174, v153
	v_mov_b32_e32 v176, v183
	v_mov_b32_e32 v180, v182
	s_waitcnt vmcnt(0)
	v_mfma_f32_32x32x16_bf16 v[32:47], v[196:199], v[174:177], v[32:47]
	ds_read2_b32 v[152:153], v184 offset0:64 offset1:96
	ds_read2_b32 v[174:175], v184 offset0:192 offset1:224
	ds_read2_b32 v[182:183], v185 offset0:64 offset1:96
	ds_read2_b32 v[176:177], v185 offset0:192 offset1:224
	v_mfma_f32_32x32x16_bf16 v[48:63], v[196:199], v[178:181], v[48:63]
	s_waitcnt lgkmcnt(3)
	v_mov_b32_e32 v178, v152
	s_waitcnt lgkmcnt(2)
	v_mov_b32_e32 v179, v174
	s_waitcnt lgkmcnt(1)
	v_mov_b32_e32 v180, v182
	s_waitcnt lgkmcnt(0)
	v_mov_b32_e32 v181, v176
	v_mov_b32_e32 v174, v153
	v_mov_b32_e32 v176, v183
	v_mfma_f32_32x32x16_bf16 v[16:31], v[196:199], v[178:181], v[16:31]
	s_nop 0
	v_mfma_f32_32x32x16_bf16 v[0:15], v[196:199], v[174:177], v[0:15]
	s_cbranch_scc1 .LBB0_1229
	global_load_dwordx2 v[188:189], v[66:67], off
	global_load_dwordx2 v[190:191], v[68:69], off
	global_load_dwordx2 v[192:193], v[70:71], off
	global_load_dwordx2 v[194:195], v[72:73], off
	global_load_dwordx2 v[196:197], v[74:75], off
	global_load_dwordx2 v[198:199], v[76:77], off
	global_load_dwordx2 v[200:201], v[78:79], off
	global_load_dwordx2 v[202:203], v[80:81], off
	global_load_dwordx2 v[204:205], v[82:83], off
	global_load_dwordx2 v[206:207], v[84:85], off
	global_load_dwordx2 v[224:225], v[86:87], off
	global_load_dwordx2 v[226:227], v[88:89], off
	global_load_dwordx2 v[228:229], v[90:91], off
	global_load_dwordx2 v[230:231], v[92:93], off
	global_load_dwordx2 v[232:233], v[94:95], off
	global_load_dwordx2 v[234:235], v[96:97], off
	s_mov_b64 s[0:1], s[8:9]
	s_lshl_b32 s4, s6, 5
	s_lshl_b32 s5, s6, 2
	s_and_b32 s4, s4, 0xffffe000
	s_and_b32 s5, s5, 0x3fc
	s_waitcnt vmcnt(15)
	v_mul_f32_e32 v169, v49, v189
	v_fmac_f32_e32 v169, v48, v188
	v_mul_f32_e32 v48, v48, v189
	v_fma_f32 v48, v49, v188, -v48
	v_bfe_u32 v49, v169, 16, 1
	v_add3_u32 v49, v169, v49, s94
	v_bfe_u32 v152, v48, 16, 1
	v_lshrrev_b32_e32 v49, 16, v49
	v_add3_u32 v48, v48, v152, s94
	v_and_or_b32 v48, v48, s86, v49
	v_add_u32_e32 v49, v156, v158
	ds_write_b32 v49, v48
	global_load_dwordx2 v[188:189], v[98:99], off
	s_waitcnt vmcnt(15)
	v_mul_f32_e32 v152, v51, v191
	v_fmac_f32_e32 v152, v50, v190
	v_mul_f32_e32 v49, v50, v191
	v_fma_f32 v48, v51, v190, -v49
	v_bfe_u32 v49, v152, 16, 1
	v_add3_u32 v49, v152, v49, s94
	v_bfe_u32 v50, v48, 16, 1
	v_lshrrev_b32_e32 v49, 16, v49
	v_add3_u32 v48, v48, v50, s94
	v_and_or_b32 v48, v48, s86, v49
	v_add_u32_e32 v49, v156, v159
	ds_write_b32 v49, v48
	global_load_dwordx2 v[190:191], v[100:101], off
	s_waitcnt vmcnt(15)
	v_mul_f32_e32 v50, v53, v193
	v_fmac_f32_e32 v50, v52, v192
	v_mul_f32_e32 v49, v52, v193
	v_fma_f32 v48, v53, v192, -v49
	v_bfe_u32 v49, v50, 16, 1
	v_add3_u32 v49, v50, v49, s94
	v_bfe_u32 v50, v48, 16, 1
	v_lshrrev_b32_e32 v49, 16, v49
	v_add3_u32 v48, v48, v50, s94
	v_and_or_b32 v48, v48, s86, v49
	v_add_u32_e32 v49, v156, v160
	ds_write_b32 v49, v48
	global_load_dwordx2 v[192:193], v[102:103], off
	s_waitcnt vmcnt(15)
	v_mul_f32_e32 v50, v55, v195
	v_fmac_f32_e32 v50, v54, v194
	v_mul_f32_e32 v49, v54, v195
	v_fma_f32 v48, v55, v194, -v49
	v_bfe_u32 v49, v50, 16, 1
	v_add3_u32 v49, v50, v49, s94
	v_bfe_u32 v50, v48, 16, 1
	v_lshrrev_b32_e32 v49, 16, v49
	v_add3_u32 v48, v48, v50, s94
	v_and_or_b32 v48, v48, s86, v49
	v_add_u32_e32 v49, v156, v161
	ds_write_b32 v49, v48
	global_load_dwordx2 v[194:195], v[104:105], off
	s_waitcnt vmcnt(15)
	v_mul_f32_e32 v50, v57, v197
	v_fmac_f32_e32 v50, v56, v196
	v_mul_f32_e32 v49, v56, v197
	v_fma_f32 v48, v57, v196, -v49
	v_bfe_u32 v49, v50, 16, 1
	v_add3_u32 v49, v50, v49, s94
	v_bfe_u32 v50, v48, 16, 1
	v_lshrrev_b32_e32 v49, 16, v49
	v_add3_u32 v48, v48, v50, s94
	v_and_or_b32 v48, v48, s86, v49
	v_add_u32_e32 v49, v156, v162
	ds_write_b32 v49, v48
	global_load_dwordx2 v[196:197], v[106:107], off
	s_waitcnt vmcnt(15)
	v_mul_f32_e32 v50, v59, v199
	v_fmac_f32_e32 v50, v58, v198
	v_mul_f32_e32 v49, v58, v199
	v_fma_f32 v48, v59, v198, -v49
	v_bfe_u32 v49, v50, 16, 1
	v_add3_u32 v49, v50, v49, s94
	v_bfe_u32 v50, v48, 16, 1
	v_lshrrev_b32_e32 v49, 16, v49
	v_add3_u32 v48, v48, v50, s94
	v_and_or_b32 v48, v48, s86, v49
	v_add_u32_e32 v49, v156, v163
	ds_write_b32 v49, v48
	global_load_dwordx2 v[198:199], v[108:109], off
	s_waitcnt vmcnt(15)
	v_mul_f32_e32 v50, v61, v201
	v_fmac_f32_e32 v50, v60, v200
	v_mul_f32_e32 v49, v60, v201
	v_fma_f32 v48, v61, v200, -v49
	v_bfe_u32 v49, v50, 16, 1
	v_add3_u32 v49, v50, v49, s94
	v_bfe_u32 v50, v48, 16, 1
	v_lshrrev_b32_e32 v49, 16, v49
	v_add3_u32 v48, v48, v50, s94
	v_and_or_b32 v48, v48, s86, v49
	v_add_u32_e32 v49, v156, v164
	ds_write_b32 v49, v48
	global_load_dwordx2 v[200:201], v[110:111], off
	s_waitcnt vmcnt(15)
	v_mul_f32_e32 v50, v63, v203
	v_fmac_f32_e32 v50, v62, v202
	v_mul_f32_e32 v49, v62, v203
	v_fma_f32 v48, v63, v202, -v49
	v_bfe_u32 v49, v50, 16, 1
	v_add3_u32 v49, v50, v49, s94
	v_bfe_u32 v50, v48, 16, 1
	v_lshrrev_b32_e32 v49, 16, v49
	v_add3_u32 v48, v48, v50, s94
	v_and_or_b32 v48, v48, s86, v49
	v_add_u32_e32 v49, v156, v165
	ds_write_b32 v49, v48
	global_load_dwordx2 v[202:203], v[112:113], off
	s_waitcnt vmcnt(15)
	v_mul_f32_e32 v50, v33, v205
	v_fmac_f32_e32 v50, v32, v204
	v_mul_f32_e32 v32, v32, v205
	v_fma_f32 v32, v33, v204, -v32
	v_bfe_u32 v33, v50, 16, 1
	v_add3_u32 v33, v50, v33, s94
	v_bfe_u32 v48, v32, 16, 1
	v_lshrrev_b32_e32 v33, 16, v33
	v_add3_u32 v32, v32, v48, s94
	v_and_or_b32 v32, v32, s86, v33
	v_add_u32_e32 v33, v166, v158
	ds_write_b32 v33, v32
	global_load_dwordx2 v[204:205], v[114:115], off
	s_waitcnt vmcnt(15)
	v_mul_f32_e32 v48, v35, v207
	v_fmac_f32_e32 v48, v34, v206
	v_mul_f32_e32 v33, v34, v207
	v_fma_f32 v32, v35, v206, -v33
	v_bfe_u32 v33, v48, 16, 1
	v_add3_u32 v33, v48, v33, s94
	v_bfe_u32 v34, v32, 16, 1
	v_lshrrev_b32_e32 v33, 16, v33
	v_add3_u32 v32, v32, v34, s94
	v_and_or_b32 v32, v32, s86, v33
	v_add_u32_e32 v33, v166, v159
	ds_write_b32 v33, v32
	global_load_dwordx2 v[206:207], v[116:117], off
	s_waitcnt vmcnt(15)
	v_mul_f32_e32 v34, v37, v225
	v_fmac_f32_e32 v34, v36, v224
	v_mul_f32_e32 v33, v36, v225
	v_fma_f32 v32, v37, v224, -v33
	v_bfe_u32 v33, v34, 16, 1
	v_add3_u32 v33, v34, v33, s94
	v_bfe_u32 v34, v32, 16, 1
	v_lshrrev_b32_e32 v33, 16, v33
	v_add3_u32 v32, v32, v34, s94
	v_and_or_b32 v32, v32, s86, v33
	v_add_u32_e32 v33, v166, v160
	ds_write_b32 v33, v32
	global_load_dwordx2 v[224:225], v[118:119], off
	s_waitcnt vmcnt(15)
	v_mul_f32_e32 v34, v39, v227
	v_fmac_f32_e32 v34, v38, v226
	v_mul_f32_e32 v33, v38, v227
	v_fma_f32 v32, v39, v226, -v33
	v_bfe_u32 v33, v34, 16, 1
	v_add3_u32 v33, v34, v33, s94
	v_bfe_u32 v34, v32, 16, 1
	v_lshrrev_b32_e32 v33, 16, v33
	v_add3_u32 v32, v32, v34, s94
	v_and_or_b32 v32, v32, s86, v33
	v_add_u32_e32 v33, v166, v161
	ds_write_b32 v33, v32
	global_load_dwordx2 v[226:227], v[120:121], off
	s_waitcnt vmcnt(15)
	v_mul_f32_e32 v34, v41, v229
	v_fmac_f32_e32 v34, v40, v228
	v_mul_f32_e32 v33, v40, v229
	v_fma_f32 v32, v41, v228, -v33
	v_bfe_u32 v33, v34, 16, 1
	v_add3_u32 v33, v34, v33, s94
	v_bfe_u32 v34, v32, 16, 1
	v_lshrrev_b32_e32 v33, 16, v33
	v_add3_u32 v32, v32, v34, s94
	v_and_or_b32 v32, v32, s86, v33
	v_add_u32_e32 v33, v166, v162
	ds_write_b32 v33, v32
	global_load_dwordx2 v[228:229], v[122:123], off
	s_waitcnt vmcnt(15)
	v_mul_f32_e32 v34, v43, v231
	v_fmac_f32_e32 v34, v42, v230
	v_mul_f32_e32 v33, v42, v231
	v_fma_f32 v32, v43, v230, -v33
	v_bfe_u32 v33, v34, 16, 1
	v_add3_u32 v33, v34, v33, s94
	v_bfe_u32 v34, v32, 16, 1
	v_lshrrev_b32_e32 v33, 16, v33
	v_add3_u32 v32, v32, v34, s94
	v_and_or_b32 v32, v32, s86, v33
	v_add_u32_e32 v33, v166, v163
	ds_write_b32 v33, v32
	global_load_dwordx2 v[230:231], v[124:125], off
	s_waitcnt vmcnt(15)
	v_mul_f32_e32 v34, v45, v233
	v_fmac_f32_e32 v34, v44, v232
	v_mul_f32_e32 v33, v44, v233
	v_fma_f32 v32, v45, v232, -v33
	v_bfe_u32 v33, v34, 16, 1
	v_add3_u32 v33, v34, v33, s94
	v_bfe_u32 v34, v32, 16, 1
	v_lshrrev_b32_e32 v33, 16, v33
	v_add3_u32 v32, v32, v34, s94
	v_and_or_b32 v32, v32, s86, v33
	v_add_u32_e32 v33, v166, v164
	ds_write_b32 v33, v32
	global_load_dwordx2 v[232:233], v[126:127], off
	s_waitcnt vmcnt(15)
	v_mul_f32_e32 v34, v47, v235
	v_fmac_f32_e32 v34, v46, v234
	v_mul_f32_e32 v33, v46, v235
	v_fma_f32 v32, v47, v234, -v33
	v_bfe_u32 v33, v34, 16, 1
	v_add3_u32 v33, v34, v33, s94
	v_bfe_u32 v34, v32, 16, 1
	v_lshrrev_b32_e32 v33, 16, v33
	v_add3_u32 v32, v32, v34, s94
	v_and_or_b32 v32, v32, s86, v33
	v_add_u32_e32 v33, v166, v165
	ds_write_b32 v33, v32
	global_load_dwordx2 v[234:235], v[128:129], off
	s_waitcnt vmcnt(15)
	v_mul_f32_e32 v34, v17, v189
	v_fmac_f32_e32 v34, v16, v188
	v_mul_f32_e32 v16, v16, v189
	v_fma_f32 v16, v17, v188, -v16
	v_bfe_u32 v17, v34, 16, 1
	v_add3_u32 v17, v34, v17, s94
	v_bfe_u32 v32, v16, 16, 1
	v_lshrrev_b32_e32 v17, 16, v17
	v_add3_u32 v16, v16, v32, s94
	v_and_or_b32 v16, v16, s86, v17
	v_add_u32_e32 v17, v167, v158
	ds_write_b32 v17, v16
	s_waitcnt vmcnt(14)
	v_mul_f32_e32 v32, v19, v191
	v_fmac_f32_e32 v32, v18, v190
	v_mul_f32_e32 v17, v18, v191
	v_fma_f32 v16, v19, v190, -v17
	v_bfe_u32 v17, v32, 16, 1
	v_add3_u32 v17, v32, v17, s94
	v_bfe_u32 v18, v16, 16, 1
	v_lshrrev_b32_e32 v17, 16, v17
	v_add3_u32 v16, v16, v18, s94
	v_and_or_b32 v16, v16, s86, v17
	v_add_u32_e32 v17, v167, v159
	ds_write_b32 v17, v16
	s_waitcnt vmcnt(13)
	v_mul_f32_e32 v18, v21, v193
	v_fmac_f32_e32 v18, v20, v192
	v_mul_f32_e32 v17, v20, v193
	v_fma_f32 v16, v21, v192, -v17
	v_bfe_u32 v17, v18, 16, 1
	v_add3_u32 v17, v18, v17, s94
	v_bfe_u32 v18, v16, 16, 1
	v_lshrrev_b32_e32 v17, 16, v17
	v_add3_u32 v16, v16, v18, s94
	v_and_or_b32 v16, v16, s86, v17
	v_add_u32_e32 v17, v167, v160
	ds_write_b32 v17, v16
	s_waitcnt vmcnt(12)
	v_mul_f32_e32 v18, v23, v195
	v_fmac_f32_e32 v18, v22, v194
	v_mul_f32_e32 v17, v22, v195
	v_fma_f32 v16, v23, v194, -v17
	v_bfe_u32 v17, v18, 16, 1
	v_add3_u32 v17, v18, v17, s94
	v_bfe_u32 v18, v16, 16, 1
	v_lshrrev_b32_e32 v17, 16, v17
	v_add3_u32 v16, v16, v18, s94
	v_and_or_b32 v16, v16, s86, v17
	v_add_u32_e32 v17, v167, v161
	ds_write_b32 v17, v16
	s_waitcnt vmcnt(11)
	v_mul_f32_e32 v18, v25, v197
	v_fmac_f32_e32 v18, v24, v196
	v_mul_f32_e32 v17, v24, v197
	v_fma_f32 v16, v25, v196, -v17
	v_bfe_u32 v17, v18, 16, 1
	v_add3_u32 v17, v18, v17, s94
	v_bfe_u32 v18, v16, 16, 1
	v_lshrrev_b32_e32 v17, 16, v17
	v_add3_u32 v16, v16, v18, s94
	v_and_or_b32 v16, v16, s86, v17
	v_add_u32_e32 v17, v167, v162
	ds_write_b32 v17, v16
	s_waitcnt vmcnt(10)
	v_mul_f32_e32 v18, v27, v199
	v_fmac_f32_e32 v18, v26, v198
	v_mul_f32_e32 v17, v26, v199
	v_fma_f32 v16, v27, v198, -v17
	v_bfe_u32 v17, v18, 16, 1
	v_add3_u32 v17, v18, v17, s94
	v_bfe_u32 v18, v16, 16, 1
	v_lshrrev_b32_e32 v17, 16, v17
	v_add3_u32 v16, v16, v18, s94
	v_and_or_b32 v16, v16, s86, v17
	v_add_u32_e32 v17, v167, v163
	ds_write_b32 v17, v16
	s_waitcnt vmcnt(9)
	v_mul_f32_e32 v18, v29, v201
	v_fmac_f32_e32 v18, v28, v200
	v_mul_f32_e32 v17, v28, v201
	v_fma_f32 v16, v29, v200, -v17
	v_bfe_u32 v17, v18, 16, 1
	v_add3_u32 v17, v18, v17, s94
	v_bfe_u32 v18, v16, 16, 1
	v_lshrrev_b32_e32 v17, 16, v17
	v_add3_u32 v16, v16, v18, s94
	v_and_or_b32 v16, v16, s86, v17
	v_add_u32_e32 v17, v167, v164
	ds_write_b32 v17, v16
	s_waitcnt vmcnt(8)
	v_mul_f32_e32 v18, v31, v203
	v_fmac_f32_e32 v18, v30, v202
	v_mul_f32_e32 v17, v30, v203
	v_fma_f32 v16, v31, v202, -v17
	v_bfe_u32 v17, v18, 16, 1
	v_add3_u32 v17, v18, v17, s94
	v_bfe_u32 v18, v16, 16, 1
	v_lshrrev_b32_e32 v17, 16, v17
	v_add3_u32 v16, v16, v18, s94
	v_and_or_b32 v16, v16, s86, v17
	v_add_u32_e32 v17, v167, v165
	ds_write_b32 v17, v16
	s_waitcnt vmcnt(7)
	v_mul_f32_e32 v18, v1, v205
	v_fmac_f32_e32 v18, v0, v204
	v_mul_f32_e32 v0, v0, v205
	v_fma_f32 v0, v1, v204, -v0
	v_bfe_u32 v1, v18, 16, 1
	v_add3_u32 v1, v18, v1, s94
	v_bfe_u32 v16, v0, 16, 1
	v_lshrrev_b32_e32 v1, 16, v1
	v_add3_u32 v0, v0, v16, s94
	v_and_or_b32 v0, v0, s86, v1
	v_add_u32_e32 v1, v168, v158
	ds_write_b32 v1, v0
	s_waitcnt vmcnt(6)
	v_mul_f32_e32 v16, v3, v207
	v_fmac_f32_e32 v16, v2, v206
	v_mul_f32_e32 v1, v2, v207
	v_fma_f32 v0, v3, v206, -v1
	v_bfe_u32 v1, v16, 16, 1
	v_add3_u32 v1, v16, v1, s94
	v_bfe_u32 v2, v0, 16, 1
	v_lshrrev_b32_e32 v1, 16, v1
	v_add3_u32 v0, v0, v2, s94
	v_and_or_b32 v0, v0, s86, v1
	v_add_u32_e32 v1, v168, v159
	ds_write_b32 v1, v0
	s_waitcnt vmcnt(5)
	v_mul_f32_e32 v2, v5, v225
	v_fmac_f32_e32 v2, v4, v224
	v_mul_f32_e32 v1, v4, v225
	v_fma_f32 v0, v5, v224, -v1
	v_bfe_u32 v1, v2, 16, 1
	v_add3_u32 v1, v2, v1, s94
	v_bfe_u32 v2, v0, 16, 1
	v_lshrrev_b32_e32 v1, 16, v1
	v_add3_u32 v0, v0, v2, s94
	v_and_or_b32 v0, v0, s86, v1
	v_add_u32_e32 v1, v168, v160
	ds_write_b32 v1, v0
	s_waitcnt vmcnt(4)
	v_mul_f32_e32 v2, v7, v227
	v_fmac_f32_e32 v2, v6, v226
	v_mul_f32_e32 v1, v6, v227
	v_fma_f32 v0, v7, v226, -v1
	v_bfe_u32 v1, v2, 16, 1
	v_add3_u32 v1, v2, v1, s94
	v_bfe_u32 v2, v0, 16, 1
	v_lshrrev_b32_e32 v1, 16, v1
	v_add3_u32 v0, v0, v2, s94
	v_and_or_b32 v0, v0, s86, v1
	v_add_u32_e32 v1, v168, v161
	ds_write_b32 v1, v0
	s_waitcnt vmcnt(3)
	v_mul_f32_e32 v2, v9, v229
	v_fmac_f32_e32 v2, v8, v228
	v_mul_f32_e32 v1, v8, v229
	v_fma_f32 v0, v9, v228, -v1
	v_bfe_u32 v1, v2, 16, 1
	v_add3_u32 v1, v2, v1, s94
	v_bfe_u32 v2, v0, 16, 1
	v_lshrrev_b32_e32 v1, 16, v1
	v_add3_u32 v0, v0, v2, s94
	v_and_or_b32 v0, v0, s86, v1
	v_add_u32_e32 v1, v168, v162
	ds_write_b32 v1, v0
	s_waitcnt vmcnt(2)
	v_mul_f32_e32 v2, v11, v231
	v_fmac_f32_e32 v2, v10, v230
	v_mul_f32_e32 v1, v10, v231
	v_fma_f32 v0, v11, v230, -v1
	v_bfe_u32 v1, v2, 16, 1
	v_add3_u32 v1, v2, v1, s94
	v_bfe_u32 v2, v0, 16, 1
	v_lshrrev_b32_e32 v1, 16, v1
	v_add3_u32 v0, v0, v2, s94
	v_and_or_b32 v0, v0, s86, v1
	v_add_u32_e32 v1, v168, v163
	ds_write_b32 v1, v0
	s_waitcnt vmcnt(1)
	v_mul_f32_e32 v2, v13, v233
	v_fmac_f32_e32 v2, v12, v232
	v_mul_f32_e32 v1, v12, v233
	v_fma_f32 v0, v13, v232, -v1
	v_bfe_u32 v1, v2, 16, 1
	v_add3_u32 v1, v2, v1, s94
	v_bfe_u32 v2, v0, 16, 1
	v_lshrrev_b32_e32 v1, 16, v1
	v_add3_u32 v0, v0, v2, s94
	v_and_or_b32 v0, v0, s86, v1
	v_add_u32_e32 v1, v168, v164
	ds_write_b32 v1, v0
	s_waitcnt vmcnt(0)
	v_mul_f32_e32 v2, v15, v235
	v_fmac_f32_e32 v2, v14, v234
	v_mul_f32_e32 v1, v14, v235
	v_fma_f32 v0, v15, v234, -v1
	v_bfe_u32 v1, v2, 16, 1
	v_add3_u32 v1, v2, v1, s94
	v_bfe_u32 v2, v0, 16, 1
	v_lshrrev_b32_e32 v1, 16, v1
	v_add3_u32 v0, v0, v2, s94
	v_and_or_b32 v0, v0, s86, v1
	v_add_u32_e32 v1, v168, v165
	ds_write_b32 v1, v0
	s_waitcnt lgkmcnt(0)
	s_barrier
	global_load_dwordx4 v[40:43], v[130:131], off
	global_load_dwordx4 v[44:47], v[132:133], off
	global_load_dwordx4 v[48:51], v[130:131], off offset:32
	global_load_dwordx4 v[52:55], v[134:135], off
	global_load_dwordx4 v[56:59], v[130:131], off offset:64
	global_load_dwordx4 v[60:63], v[136:137], off
	global_load_dwordx4 v[172:175], v[130:131], off offset:96
	global_load_dwordx4 v[176:179], v[138:139], off
	global_load_dwordx4 v[180:183], v[130:131], off offset:128
	global_load_dwordx4 v[184:187], v[140:141], off
	global_load_dwordx4 v[188:191], v[130:131], off offset:160
	global_load_dwordx4 v[192:195], v[142:143], off
	global_load_dwordx4 v[196:199], v[130:131], off offset:192
	global_load_dwordx4 v[200:203], v[144:145], off
	global_load_dwordx4 v[204:207], v[130:131], off offset:224
	global_load_dwordx4 v[224:227], v[146:147], off
	ds_read_b128 v[4:7], v65
	ds_read_b128 v[32:35], v65 offset:32
	s_waitcnt vmcnt(15) lgkmcnt(1)
	v_mfma_f32_32x32x16_bf16 v[16:31], v[40:43], v[4:7], 0
	s_waitcnt vmcnt(13) lgkmcnt(0)
	v_mfma_f32_32x32x16_bf16 v[16:31], v[48:51], v[32:35], v[16:31]
	v_mfma_f32_32x32x16_bf16 v[0:15], v[44:47], v[4:7], 0
	s_waitcnt vmcnt(12)
	v_mfma_f32_32x32x16_bf16 v[0:15], v[52:55], v[32:35], v[0:15]
	ds_read_b128 v[32:35], v65 offset:64
	s_waitcnt vmcnt(11) lgkmcnt(0)
	v_mfma_f32_32x32x16_bf16 v[16:31], v[56:59], v[32:35], v[16:31]
	s_waitcnt vmcnt(10)
	v_mfma_f32_32x32x16_bf16 v[0:15], v[60:63], v[32:35], v[0:15]
	ds_read_b128 v[32:35], v65 offset:96
	s_waitcnt vmcnt(9) lgkmcnt(0)
	v_mfma_f32_32x32x16_bf16 v[16:31], v[172:175], v[32:35], v[16:31]
	s_waitcnt vmcnt(8)
	v_mfma_f32_32x32x16_bf16 v[0:15], v[176:179], v[32:35], v[0:15]
	ds_read_b128 v[32:35], v65 offset:128
	s_waitcnt vmcnt(7) lgkmcnt(0)
	v_mfma_f32_32x32x16_bf16 v[16:31], v[180:183], v[32:35], v[16:31]
	s_waitcnt vmcnt(6)
	v_mfma_f32_32x32x16_bf16 v[0:15], v[184:187], v[32:35], v[0:15]
	ds_read_b128 v[32:35], v65 offset:160
	s_waitcnt vmcnt(5) lgkmcnt(0)
	v_mfma_f32_32x32x16_bf16 v[16:31], v[188:191], v[32:35], v[16:31]
	s_waitcnt vmcnt(4)
	v_mfma_f32_32x32x16_bf16 v[0:15], v[192:195], v[32:35], v[0:15]
	ds_read_b128 v[32:35], v65 offset:192
	s_waitcnt vmcnt(3) lgkmcnt(0)
	v_mfma_f32_32x32x16_bf16 v[16:31], v[196:199], v[32:35], v[16:31]
	s_waitcnt vmcnt(2)
	v_mfma_f32_32x32x16_bf16 v[0:15], v[200:203], v[32:35], v[0:15]
	ds_read_b128 v[32:35], v65 offset:224
	s_waitcnt vmcnt(1) lgkmcnt(0)
	v_mfma_f32_32x32x16_bf16 v[16:31], v[204:207], v[32:35], v[16:31]
	s_nop 11
	v_mul_f32_e32 v16, 0x3a800000, v16
	s_waitcnt vmcnt(0)
	v_mfma_f32_32x32x16_bf16 v[0:15], v[224:227], v[32:35], v[0:15]
	v_mov_b32_e32 v34, v154
	s_add_u32 s0, s0, s5
	v_and_or_b32 v32, v34, 30, s12
	v_ashrrev_i32_e32 v35, 1, v32
	v_and_b32_e32 v32, 1, v34
	v_lshlrev_b32_e32 v34, 4, v34
	v_and_b32_e32 v34, 0xfffffe00, v34
	s_addc_u32 s1, s1, 0
	v_lshlrev_b32_e32 v208, 1, v32
	v_add3_u32 v34, v35, s4, v34
	v_lshl_add_u64 v[32:33], s[0:1], 0, v[208:209]
	s_mov_b64 s[0:1], 0xf900000
	v_bfe_u32 v36, v16, 16, 1
	v_ashrrev_i32_e32 v35, 31, v34
	v_lshl_add_u64 v[32:33], v[32:33], 0, s[0:1]
	v_add3_u32 v16, v16, v36, s94
	v_lshlrev_b64 v[36:37], 10, v[34:35]
	v_lshl_add_u64 v[36:37], v[32:33], 0, v[36:37]
	global_store_short_d16_hi v[36:37], v16, off
	v_mul_f32_e32 v16, 0x3a800000, v17
	v_bfe_u32 v17, v16, 16, 1
	v_add3_u32 v35, v16, v17, s94
	v_add_u32_e32 v16, 0x80, v34
	v_ashrrev_i32_e32 v17, 31, v16
	v_lshlrev_b64 v[16:17], 10, v[16:17]
	v_lshl_add_u64 v[16:17], v[32:33], 0, v[16:17]
	global_store_short_d16_hi v[16:17], v35, off
	v_mul_f32_e32 v16, 0x3a800000, v18
	v_bfe_u32 v17, v16, 16, 1
	v_add3_u32 v18, v16, v17, s94
	v_add_u32_e32 v16, 0x100, v34
	v_ashrrev_i32_e32 v17, 31, v16
	v_lshlrev_b64 v[16:17], 10, v[16:17]
	v_lshl_add_u64 v[16:17], v[32:33], 0, v[16:17]
	global_store_short_d16_hi v[16:17], v18, off
	v_mul_f32_e32 v16, 0x3a800000, v19
	v_bfe_u32 v17, v16, 16, 1
	v_add3_u32 v18, v16, v17, s94
	v_add_u32_e32 v16, 0x180, v34
	v_ashrrev_i32_e32 v17, 31, v16
	v_lshlrev_b64 v[16:17], 10, v[16:17]
	v_lshl_add_u64 v[16:17], v[32:33], 0, v[16:17]
	global_store_short_d16_hi v[16:17], v18, off
	v_mul_f32_e32 v16, 0x3a800000, v20
	v_bfe_u32 v17, v16, 16, 1
	v_add3_u32 v18, v16, v17, s94
	v_add_u32_e32 v16, 0x400, v34
	v_ashrrev_i32_e32 v17, 31, v16
	v_lshlrev_b64 v[16:17], 10, v[16:17]
	v_lshl_add_u64 v[16:17], v[32:33], 0, v[16:17]
	global_store_short_d16_hi v[16:17], v18, off
	v_mul_f32_e32 v16, 0x3a800000, v21
	v_bfe_u32 v17, v16, 16, 1
	v_add3_u32 v18, v16, v17, s94
	v_add_u32_e32 v16, 0x480, v34
	v_ashrrev_i32_e32 v17, 31, v16
	v_lshlrev_b64 v[16:17], 10, v[16:17]
	v_lshl_add_u64 v[16:17], v[32:33], 0, v[16:17]
	global_store_short_d16_hi v[16:17], v18, off
	v_mul_f32_e32 v16, 0x3a800000, v22
	v_bfe_u32 v17, v16, 16, 1
	v_add3_u32 v18, v16, v17, s94
	v_add_u32_e32 v16, 0x500, v34
	v_ashrrev_i32_e32 v17, 31, v16
	v_lshlrev_b64 v[16:17], 10, v[16:17]
	v_lshl_add_u64 v[16:17], v[32:33], 0, v[16:17]
	global_store_short_d16_hi v[16:17], v18, off
	v_mul_f32_e32 v16, 0x3a800000, v23
	v_bfe_u32 v17, v16, 16, 1
	v_add3_u32 v18, v16, v17, s94
	v_add_u32_e32 v16, 0x580, v34
	v_ashrrev_i32_e32 v17, 31, v16
	v_lshlrev_b64 v[16:17], 10, v[16:17]
	v_lshl_add_u64 v[16:17], v[32:33], 0, v[16:17]
	global_store_short_d16_hi v[16:17], v18, off
	v_mul_f32_e32 v16, 0x3a800000, v24
	v_bfe_u32 v17, v16, 16, 1
	v_add3_u32 v18, v16, v17, s94
	v_add_u32_e32 v16, 0x800, v34
	v_ashrrev_i32_e32 v17, 31, v16
	v_lshlrev_b64 v[16:17], 10, v[16:17]
	v_lshl_add_u64 v[16:17], v[32:33], 0, v[16:17]
	global_store_short_d16_hi v[16:17], v18, off
	v_mul_f32_e32 v16, 0x3a800000, v25
	v_bfe_u32 v17, v16, 16, 1
	v_add3_u32 v18, v16, v17, s94
	v_add_u32_e32 v16, 0x880, v34
	v_ashrrev_i32_e32 v17, 31, v16
	v_lshlrev_b64 v[16:17], 10, v[16:17]
	v_lshl_add_u64 v[16:17], v[32:33], 0, v[16:17]
	global_store_short_d16_hi v[16:17], v18, off
	v_mul_f32_e32 v16, 0x3a800000, v26
	v_bfe_u32 v17, v16, 16, 1
	v_add3_u32 v18, v16, v17, s94
	v_add_u32_e32 v16, 0x900, v34
	v_ashrrev_i32_e32 v17, 31, v16
	v_lshlrev_b64 v[16:17], 10, v[16:17]
	v_lshl_add_u64 v[16:17], v[32:33], 0, v[16:17]
	global_store_short_d16_hi v[16:17], v18, off
	v_mul_f32_e32 v16, 0x3a800000, v27
	v_bfe_u32 v17, v16, 16, 1
	v_add3_u32 v18, v16, v17, s94
	v_add_u32_e32 v16, 0x980, v34
	v_ashrrev_i32_e32 v17, 31, v16
	v_lshlrev_b64 v[16:17], 10, v[16:17]
	v_lshl_add_u64 v[16:17], v[32:33], 0, v[16:17]
	global_store_short_d16_hi v[16:17], v18, off
	v_mul_f32_e32 v16, 0x3a800000, v28
	v_bfe_u32 v17, v16, 16, 1
	v_add3_u32 v18, v16, v17, s94
	v_add_u32_e32 v16, 0xc00, v34
	v_ashrrev_i32_e32 v17, 31, v16
	v_lshlrev_b64 v[16:17], 10, v[16:17]
	v_lshl_add_u64 v[16:17], v[32:33], 0, v[16:17]
	global_store_short_d16_hi v[16:17], v18, off
	v_mul_f32_e32 v16, 0x3a800000, v29
	v_bfe_u32 v17, v16, 16, 1
	v_add3_u32 v18, v16, v17, s94
	v_add_u32_e32 v16, 0xc80, v34
	v_ashrrev_i32_e32 v17, 31, v16
	v_lshlrev_b64 v[16:17], 10, v[16:17]
	v_lshl_add_u64 v[16:17], v[32:33], 0, v[16:17]
	global_store_short_d16_hi v[16:17], v18, off
	v_mul_f32_e32 v16, 0x3a800000, v30
	v_bfe_u32 v17, v16, 16, 1
	v_add3_u32 v18, v16, v17, s94
	v_add_u32_e32 v16, 0xd00, v34
	v_ashrrev_i32_e32 v17, 31, v16
	v_lshlrev_b64 v[16:17], 10, v[16:17]
	v_lshl_add_u64 v[16:17], v[32:33], 0, v[16:17]
	global_store_short_d16_hi v[16:17], v18, off
	v_mul_f32_e32 v16, 0x3a800000, v31
	v_bfe_u32 v17, v16, 16, 1
	v_add3_u32 v18, v16, v17, s94
	v_add_u32_e32 v16, 0xd80, v34
	v_ashrrev_i32_e32 v17, 31, v16
	v_lshlrev_b64 v[16:17], 10, v[16:17]
	v_lshl_add_u64 v[16:17], v[32:33], 0, v[16:17]
	v_mul_f32_e32 v0, 0x3a800000, v0
	global_store_short_d16_hi v[16:17], v18, off
	v_bfe_u32 v16, v0, 16, 1
	v_add3_u32 v0, v0, v16, s94
	v_add_u32_e32 v16, 0x1000, v34
	v_ashrrev_i32_e32 v17, 31, v16
	v_lshlrev_b64 v[16:17], 10, v[16:17]
	v_lshl_add_u64 v[16:17], v[32:33], 0, v[16:17]
	global_store_short_d16_hi v[16:17], v0, off
	v_mul_f32_e32 v0, 0x3a800000, v1
	v_bfe_u32 v1, v0, 16, 1
	v_add3_u32 v16, v0, v1, s94
	v_add_u32_e32 v0, 0x1080, v34
	v_ashrrev_i32_e32 v1, 31, v0
	v_lshlrev_b64 v[0:1], 10, v[0:1]
	v_lshl_add_u64 v[0:1], v[32:33], 0, v[0:1]
	global_store_short_d16_hi v[0:1], v16, off
	v_mul_f32_e32 v0, 0x3a800000, v2
	v_bfe_u32 v1, v0, 16, 1
	v_add3_u32 v2, v0, v1, s94
	v_add_u32_e32 v0, 0x1100, v34
	v_ashrrev_i32_e32 v1, 31, v0
	v_lshlrev_b64 v[0:1], 10, v[0:1]
	v_lshl_add_u64 v[0:1], v[32:33], 0, v[0:1]
	global_store_short_d16_hi v[0:1], v2, off
	v_mul_f32_e32 v0, 0x3a800000, v3
	v_bfe_u32 v1, v0, 16, 1
	v_add3_u32 v2, v0, v1, s94
	v_add_u32_e32 v0, 0x1180, v34
	v_ashrrev_i32_e32 v1, 31, v0
	v_lshlrev_b64 v[0:1], 10, v[0:1]
	v_lshl_add_u64 v[0:1], v[32:33], 0, v[0:1]
	global_store_short_d16_hi v[0:1], v2, off
	v_mul_f32_e32 v0, 0x3a800000, v4
	v_bfe_u32 v1, v0, 16, 1
	v_add3_u32 v2, v0, v1, s94
	v_add_u32_e32 v0, 0x1400, v34
	v_ashrrev_i32_e32 v1, 31, v0
	v_lshlrev_b64 v[0:1], 10, v[0:1]
	v_lshl_add_u64 v[0:1], v[32:33], 0, v[0:1]
	global_store_short_d16_hi v[0:1], v2, off
	v_mul_f32_e32 v0, 0x3a800000, v5
	v_bfe_u32 v1, v0, 16, 1
	v_add3_u32 v2, v0, v1, s94
	v_add_u32_e32 v0, 0x1480, v34
	v_ashrrev_i32_e32 v1, 31, v0
	v_lshlrev_b64 v[0:1], 10, v[0:1]
	v_lshl_add_u64 v[0:1], v[32:33], 0, v[0:1]
	global_store_short_d16_hi v[0:1], v2, off
	v_mul_f32_e32 v0, 0x3a800000, v6
	v_bfe_u32 v1, v0, 16, 1
	v_add3_u32 v2, v0, v1, s94
	v_add_u32_e32 v0, 0x1500, v34
	v_ashrrev_i32_e32 v1, 31, v0
	v_lshlrev_b64 v[0:1], 10, v[0:1]
	v_lshl_add_u64 v[0:1], v[32:33], 0, v[0:1]
	global_store_short_d16_hi v[0:1], v2, off
	v_mul_f32_e32 v0, 0x3a800000, v7
	v_bfe_u32 v1, v0, 16, 1
	v_add3_u32 v2, v0, v1, s94
	v_add_u32_e32 v0, 0x1580, v34
	v_ashrrev_i32_e32 v1, 31, v0
	v_lshlrev_b64 v[0:1], 10, v[0:1]
	v_lshl_add_u64 v[0:1], v[32:33], 0, v[0:1]
	global_store_short_d16_hi v[0:1], v2, off
	v_mul_f32_e32 v0, 0x3a800000, v8
	v_bfe_u32 v1, v0, 16, 1
	v_add3_u32 v2, v0, v1, s94
	v_add_u32_e32 v0, 0x1800, v34
	v_ashrrev_i32_e32 v1, 31, v0
	v_lshlrev_b64 v[0:1], 10, v[0:1]
	v_lshl_add_u64 v[0:1], v[32:33], 0, v[0:1]
	global_store_short_d16_hi v[0:1], v2, off
	v_mul_f32_e32 v0, 0x3a800000, v9
	v_bfe_u32 v1, v0, 16, 1
	v_add3_u32 v2, v0, v1, s94
	v_add_u32_e32 v0, 0x1880, v34
	v_ashrrev_i32_e32 v1, 31, v0
	v_lshlrev_b64 v[0:1], 10, v[0:1]
	v_lshl_add_u64 v[0:1], v[32:33], 0, v[0:1]
	global_store_short_d16_hi v[0:1], v2, off
	v_mul_f32_e32 v0, 0x3a800000, v10
	v_bfe_u32 v1, v0, 16, 1
	v_add3_u32 v2, v0, v1, s94
	v_add_u32_e32 v0, 0x1900, v34
	v_ashrrev_i32_e32 v1, 31, v0
	v_lshlrev_b64 v[0:1], 10, v[0:1]
	v_lshl_add_u64 v[0:1], v[32:33], 0, v[0:1]
	global_store_short_d16_hi v[0:1], v2, off
	v_mul_f32_e32 v0, 0x3a800000, v11
	v_bfe_u32 v1, v0, 16, 1
	v_add3_u32 v2, v0, v1, s94
	v_add_u32_e32 v0, 0x1980, v34
	v_ashrrev_i32_e32 v1, 31, v0
	v_lshlrev_b64 v[0:1], 10, v[0:1]
	v_lshl_add_u64 v[0:1], v[32:33], 0, v[0:1]
	global_store_short_d16_hi v[0:1], v2, off
	v_mul_f32_e32 v0, 0x3a800000, v12
	v_bfe_u32 v1, v0, 16, 1
	v_add3_u32 v2, v0, v1, s94
	v_add_u32_e32 v0, 0x1c00, v34
	v_ashrrev_i32_e32 v1, 31, v0
	v_lshlrev_b64 v[0:1], 10, v[0:1]
	v_lshl_add_u64 v[0:1], v[32:33], 0, v[0:1]
	global_store_short_d16_hi v[0:1], v2, off
	v_mul_f32_e32 v0, 0x3a800000, v13
	v_bfe_u32 v1, v0, 16, 1
	v_add3_u32 v2, v0, v1, s94
	v_add_u32_e32 v0, 0x1c80, v34
	v_ashrrev_i32_e32 v1, 31, v0
	v_lshlrev_b64 v[0:1], 10, v[0:1]
	v_lshl_add_u64 v[0:1], v[32:33], 0, v[0:1]
	global_store_short_d16_hi v[0:1], v2, off
	v_mul_f32_e32 v0, 0x3a800000, v14
	v_bfe_u32 v1, v0, 16, 1
	v_add3_u32 v2, v0, v1, s94
	v_add_u32_e32 v0, 0x1d00, v34
	v_ashrrev_i32_e32 v1, 31, v0
	v_lshlrev_b64 v[0:1], 10, v[0:1]
	v_lshl_add_u64 v[0:1], v[32:33], 0, v[0:1]
	global_store_short_d16_hi v[0:1], v2, off
	v_mul_f32_e32 v0, 0x3a800000, v15
	v_bfe_u32 v1, v0, 16, 1
	v_add3_u32 v2, v0, v1, s94
	v_add_u32_e32 v0, 0x1d80, v34
	v_ashrrev_i32_e32 v1, 31, v0
	v_lshlrev_b64 v[0:1], 10, v[0:1]
	s_add_i32 s6, s6, s52
	v_lshl_add_u64 v[0:1], v[32:33], 0, v[0:1]
	s_cmpk_lt_i32 s6, 0x200
	global_store_short_d16_hi v[0:1], v2, off
	s_waitcnt lgkmcnt(0)
	s_barrier
	s_cbranch_scc1 .LBB0_1228
